# QKV GEMM RoPE epilogue: 8 serialised cos/sin load+wait rounds -> loads requested up front into dead fragment registers, counted vmcnt waits
# baseline (speedup 1.0000x reference)
; __device__ __forceinline__ u32x4 pack8(const f32x4 a, const f32x4 b) { u32x4 w; w.x = cvt_pk_bf16(a[0], a[1]); w.y = cvt_pk_bf16(a[2], a[3]); w.z = cvt_pk_bf16(b[0], b[1]); w.w = cvt_pk_bf16(b[2], b[3]); return w; }
;     __device__ __forceinline__ void operator()(const f32x4 (&acc)[2][2][4][2], const Unit& u, int wr, int wc, int fr, int fq) const {
;     ...
;         const int row0 = u.pm * BM + wr * 64 + fr, col0 = colt + wc * 32 + 8 * fq;
;         const int smask = (u.pm * BM < 32768) ? 2047 : 4095;
;         const int dq = 16 * (wc & 1) + 4 * fq;
; #pragma unroll
;         for (int ai = 0; ai < 2; ++ai)
; #pragma unroll
;             for (int m = 0; m < 4; ++m) { const int row = row0 + ai * HALF + m * 16; bf16_t* rowp = base + (size_t)row * ld + col0;
;                 f32x4 c = (f32x4){1.f, 1.f, 1.f, 1.f}, s = (f32x4){0.f, 0.f, 0.f, 0.f};
;                 if (rope) { const int pos = row & smask; c = *(const f32x4*)(cosT + pos * 32 + dq); s = *(const f32x4*)(sinT + pos * 32 + dq); }
; #pragma unroll
;                 for (int bj = 0; bj < 2; ++bj) { const f32x4 x1 = acc[ai][bj][m][0], x2 = acc[ai][bj][m][1];
;                     const f32x4 o1 = x1 * c - x2 * s, o2 = x2 * c + x1 * s;
;                     *(u32x4*)(rowp + bj * HALF) = pack8(o1, o2); } }
.LBB0_417:
	v_lshl_add_u32 v166, s4, 8, v1
	s_cmpk_lt_i32 s4, 0x80
	s_movk_i32 s4, 0x7ff
	v_cndmask_b32_e64 v135, 0, 1, s[52:53]
	s_cselect_b32 s26, s4, 0xfff
	v_mov_b32_e32 v138, 0
	v_mov_b32_e32 v134, 1.0
	v_cmp_ne_u32_e64 s[4:5], 1, v135
	s_andn2_b64 vcc, exec, s[52:53]
	v_mov_b32_e32 v140, 1.0
	v_mov_b32_e32 v141, 1.0
	v_mov_b32_e32 v142, 1.0
	v_mov_b32_e32 v143, 1.0
	v_mov_b32_e32 v144, 0
	v_mov_b32_e32 v145, 0
	v_mov_b32_e32 v146, 0
	v_mov_b32_e32 v147, 0
	s_cbranch_vccnz .LBB0_419
	v_and_b32_e32 v135, s26, v166
	v_lshlrev_b32_e32 v136, 7, v135
	v_mov_b32_e32 v137, v0
	v_lshl_add_u64 v[144:145], v[154:155], 0, v[136:137]
	v_lshl_add_u64 v[136:137], v[156:157], 0, v[136:137]
	global_load_dwordx4 v[140:143], v[136:137], off
	s_nop 0
	global_load_dwordx4 v[144:147], v[144:145], off
	v_add_u32_e32 v248, 0x10, v166
	v_and_b32_e32 v248, s26, v248
	v_lshlrev_b32_e32 v248, 7, v248
	v_mov_b32_e32 v249, v0
	v_lshl_add_u64 v[250:251], v[154:155], 0, v[248:249]
	v_lshl_add_u64 v[248:249], v[156:157], 0, v[248:249]
	global_load_dwordx4 v[188:191], v[248:249], off
	s_nop 0
	global_load_dwordx4 v[192:195], v[250:251], off
	v_add_u32_e32 v248, 0x20, v166
	v_and_b32_e32 v248, s26, v248
	v_lshlrev_b32_e32 v248, 7, v248
	v_mov_b32_e32 v249, v0
	v_lshl_add_u64 v[250:251], v[154:155], 0, v[248:249]
	v_lshl_add_u64 v[248:249], v[156:157], 0, v[248:249]
	global_load_dwordx4 v[196:199], v[248:249], off
	s_nop 0
	global_load_dwordx4 v[208:211], v[250:251], off
	v_add_u32_e32 v248, 0x30, v166
	v_and_b32_e32 v248, s26, v248
	v_lshlrev_b32_e32 v248, 7, v248
	v_mov_b32_e32 v249, v0
	v_lshl_add_u64 v[250:251], v[154:155], 0, v[248:249]
	v_lshl_add_u64 v[248:249], v[156:157], 0, v[248:249]
	global_load_dwordx4 v[212:215], v[248:249], off
	s_nop 0
	global_load_dwordx4 v[216:219], v[250:251], off
	v_add_u32_e32 v248, 0x80, v166
	v_and_b32_e32 v248, s26, v248
	v_lshlrev_b32_e32 v248, 7, v248
	v_mov_b32_e32 v249, v0
	v_lshl_add_u64 v[250:251], v[154:155], 0, v[248:249]
	v_lshl_add_u64 v[248:249], v[156:157], 0, v[248:249]
	global_load_dwordx4 v[220:223], v[248:249], off
	s_nop 0
	global_load_dwordx4 v[224:227], v[250:251], off
	v_add_u32_e32 v248, 0x90, v166
	v_and_b32_e32 v248, s26, v248
	v_lshlrev_b32_e32 v248, 7, v248
	v_mov_b32_e32 v249, v0
	v_lshl_add_u64 v[250:251], v[154:155], 0, v[248:249]
	v_lshl_add_u64 v[248:249], v[156:157], 0, v[248:249]
	global_load_dwordx4 v[228:231], v[248:249], off
	s_nop 0
	global_load_dwordx4 v[232:235], v[250:251], off
	v_add_u32_e32 v248, 0xa0, v166
	v_and_b32_e32 v248, s26, v248
	v_lshlrev_b32_e32 v248, 7, v248
	v_mov_b32_e32 v249, v0
	v_lshl_add_u64 v[250:251], v[154:155], 0, v[248:249]
	v_lshl_add_u64 v[248:249], v[156:157], 0, v[248:249]
	global_load_dwordx4 v[236:239], v[248:249], off
	s_nop 0
	global_load_dwordx4 v[240:243], v[250:251], off
.LBB0_419:
	v_add_u32_e32 v136, s27, v164
	s_waitcnt vmcnt(12)
	v_pk_mul_f32 v[168:169], v[128:129], v[146:147]
	v_pk_mul_f32 v[170:171], v[126:127], v[144:145]
	v_ashrrev_i32_e32 v137, 31, v136
	v_pk_fma_f32 v[168:169], v[132:133], v[142:143], v[168:169] neg_lo:[0,0,1] neg_hi:[0,0,1]
	v_pk_fma_f32 v[170:171], v[130:131], v[140:141], v[170:171] neg_lo:[0,0,1] neg_hi:[0,0,1]
	v_pk_mul_f32 v[132:133], v[132:133], v[146:147]
	v_pk_mul_f32 v[130:131], v[130:131], v[144:145]
	v_lshl_add_u64 v[162:163], v[136:137], 1, s[50:51]
	v_mad_i64_i32 v[136:137], s[50:51], s19, v166, 0
	v_pk_fma_f32 v[132:133], v[128:129], v[142:143], v[132:133]
	v_pk_fma_f32 v[128:129], v[126:127], v[140:141], v[130:131]
	v_lshl_add_u64 v[136:137], v[136:137], 1, v[162:163]
	v_cvt_pk_bf16_f32 v126, v170, v171
	v_cvt_pk_bf16_f32 v127, v168, v169
	v_cvt_pk_bf16_f32 v128, v128, v129
	v_cvt_pk_bf16_f32 v129, v132, v133
	global_store_dwordx4 v[136:137], v[126:129], off
	s_and_b64 vcc, exec, s[4:5]
	v_mov_b32_e32 v135, 1.0
	v_pk_mul_f32 v[126:127], v[120:121], v[146:147]
	v_pk_mul_f32 v[128:129], v[118:119], v[144:145]
	v_pk_fma_f32 v[126:127], v[124:125], v[142:143], v[126:127] neg_lo:[0,0,1] neg_hi:[0,0,1]
	v_pk_fma_f32 v[128:129], v[122:123], v[140:141], v[128:129] neg_lo:[0,0,1] neg_hi:[0,0,1]
	v_pk_mul_f32 v[124:125], v[124:125], v[146:147]
	v_pk_mul_f32 v[122:123], v[122:123], v[144:145]
	v_pk_fma_f32 v[124:125], v[120:121], v[142:143], v[124:125]
	v_pk_fma_f32 v[120:121], v[118:119], v[140:141], v[122:123]
	v_cvt_pk_bf16_f32 v118, v128, v129
	v_cvt_pk_bf16_f32 v119, v126, v127
	v_mov_b32_e32 v139, 0
	v_cvt_pk_bf16_f32 v120, v120, v121
	v_cvt_pk_bf16_f32 v121, v124, v125
	global_store_dwordx4 v[136:137], v[118:121], off offset:256
	v_mov_b32_e32 v136, 1.0
	v_mov_b32_e32 v137, 1.0
	v_or_b32_e32 v118, 16, v166
	v_mov_b32_e32 v140, 0
	v_mov_b32_e32 v141, 0
	s_cbranch_vccnz .LBB0_421
	s_waitcnt vmcnt(12)
	v_mov_b32_e32 v134, v188
	v_mov_b32_e32 v135, v189
	v_mov_b32_e32 v136, v190
	v_mov_b32_e32 v137, v191
	v_mov_b32_e32 v138, v192
	v_mov_b32_e32 v139, v193
	v_mov_b32_e32 v140, v194
	v_mov_b32_e32 v141, v195
	v_add_u32_e32 v248, 0xb0, v166
	v_and_b32_e32 v248, s26, v248
	v_lshlrev_b32_e32 v248, 7, v248
	v_mov_b32_e32 v249, v0
	v_lshl_add_u64 v[250:251], v[154:155], 0, v[248:249]
	v_lshl_add_u64 v[248:249], v[156:157], 0, v[248:249]
	global_load_dwordx4 v[188:191], v[248:249], off
	s_nop 0
	global_load_dwordx4 v[192:195], v[250:251], off
; __device__ __forceinline__ u32x4 pack8(const f32x4 a, const f32x4 b) { u32x4 w; w.x = cvt_pk_bf16(a[0], a[1]); w.y = cvt_pk_bf16(a[2], a[3]); w.z = cvt_pk_bf16(b[0], b[1]); w.w = cvt_pk_bf16(b[2], b[3]); return w; }
;     __device__ __forceinline__ void operator()(const f32x4 (&acc)[2][2][4][2], const Unit& u, int wr, int wc, int fr, int fq) const {
;     ...
;         for (int ai = 0; ai < 2; ++ai)
; #pragma unroll
;             for (int m = 0; m < 4; ++m) { const int row = row0 + ai * HALF + m * 16; bf16_t* rowp = base + (size_t)row * ld + col0;
;                 f32x4 c = (f32x4){1.f, 1.f, 1.f, 1.f}, s = (f32x4){0.f, 0.f, 0.f, 0.f};
;                 if (rope) { const int pos = row & smask; c = *(const f32x4*)(cosT + pos * 32 + dq); s = *(const f32x4*)(sinT + pos * 32 + dq); }
; #pragma unroll
;                 for (int bj = 0; bj < 2; ++bj) { const f32x4 x1 = acc[ai][bj][m][0], x2 = acc[ai][bj][m][1];
;                     const f32x4 o1 = x1 * c - x2 * s, o2 = x2 * c + x1 * s;
;                     *(u32x4*)(rowp + bj * HALF) = pack8(o1, o2); } }
.LBB0_421:
	v_pk_mul_f32 v[120:121], v[112:113], v[140:141]
	v_pk_mul_f32 v[122:123], v[110:111], v[138:139]
	v_pk_fma_f32 v[120:121], v[116:117], v[136:137], v[120:121] neg_lo:[0,0,1] neg_hi:[0,0,1]
	v_pk_fma_f32 v[122:123], v[114:115], v[134:135], v[122:123] neg_lo:[0,0,1] neg_hi:[0,0,1]
	v_pk_mul_f32 v[116:117], v[116:117], v[140:141]
	v_pk_mul_f32 v[114:115], v[114:115], v[138:139]
	v_mad_i64_i32 v[118:119], s[50:51], s19, v118, 0
	v_pk_fma_f32 v[116:117], v[112:113], v[136:137], v[116:117]
	v_pk_fma_f32 v[112:113], v[110:111], v[134:135], v[114:115]
	v_lshl_add_u64 v[118:119], v[118:119], 1, v[162:163]
	v_cvt_pk_bf16_f32 v110, v122, v123
	v_cvt_pk_bf16_f32 v111, v120, v121
	v_cvt_pk_bf16_f32 v112, v112, v113
	v_cvt_pk_bf16_f32 v113, v116, v117
	global_store_dwordx4 v[118:119], v[110:113], off
	s_and_b64 vcc, exec, s[4:5]
	v_mov_b32_e32 v114, 0
	v_pk_mul_f32 v[110:111], v[104:105], v[140:141]
	v_pk_mul_f32 v[112:113], v[102:103], v[138:139]
	v_pk_fma_f32 v[110:111], v[108:109], v[136:137], v[110:111] neg_lo:[0,0,1] neg_hi:[0,0,1]
	v_pk_fma_f32 v[112:113], v[106:107], v[134:135], v[112:113] neg_lo:[0,0,1] neg_hi:[0,0,1]
	v_pk_mul_f32 v[108:109], v[108:109], v[140:141]
	v_pk_mul_f32 v[106:107], v[106:107], v[138:139]
	v_pk_fma_f32 v[108:109], v[104:105], v[136:137], v[108:109]
	v_pk_fma_f32 v[104:105], v[102:103], v[134:135], v[106:107]
	v_cvt_pk_bf16_f32 v102, v112, v113
	v_cvt_pk_bf16_f32 v103, v110, v111
	v_mov_b32_e32 v106, 0
	v_cvt_pk_bf16_f32 v104, v104, v105
	v_cvt_pk_bf16_f32 v105, v108, v109
	global_store_dwordx4 v[118:119], v[102:105], off offset:256
	v_mov_b32_e32 v108, 1.0
	v_mov_b32_e32 v109, 1.0
	v_or_b32_e32 v103, 32, v166
	v_mov_b32_e32 v102, 1.0
	v_mov_b32_e32 v110, 1.0
	v_mov_b32_e32 v111, 1.0
	v_mov_b32_e32 v112, 0
	v_mov_b32_e32 v113, 0
	v_mov_b32_e32 v115, 0
	s_cbranch_vccnz .LBB0_423
	s_waitcnt vmcnt(14)
	v_mov_b32_e32 v108, v196
	v_mov_b32_e32 v109, v197
	v_mov_b32_e32 v110, v198
	v_mov_b32_e32 v111, v199
	v_mov_b32_e32 v112, v208
	v_mov_b32_e32 v113, v209
	v_mov_b32_e32 v114, v210
	v_mov_b32_e32 v115, v211
.LBB0_423:
	v_pk_mul_f32 v[116:117], v[96:97], v[114:115]
	v_pk_mul_f32 v[118:119], v[94:95], v[112:113]
	v_pk_fma_f32 v[116:117], v[100:101], v[110:111], v[116:117] neg_lo:[0,0,1] neg_hi:[0,0,1]
	v_pk_fma_f32 v[118:119], v[98:99], v[108:109], v[118:119] neg_lo:[0,0,1] neg_hi:[0,0,1]
	v_pk_mul_f32 v[100:101], v[100:101], v[114:115]
	v_pk_mul_f32 v[98:99], v[98:99], v[112:113]
	v_mad_i64_i32 v[104:105], s[50:51], s19, v103, 0
	v_pk_fma_f32 v[100:101], v[96:97], v[110:111], v[100:101]
	v_pk_fma_f32 v[96:97], v[94:95], v[108:109], v[98:99]
	v_lshl_add_u64 v[104:105], v[104:105], 1, v[162:163]
	v_cvt_pk_bf16_f32 v94, v118, v119
	v_cvt_pk_bf16_f32 v95, v116, v117
	v_cvt_pk_bf16_f32 v96, v96, v97
	v_cvt_pk_bf16_f32 v97, v100, v101
	global_store_dwordx4 v[104:105], v[94:97], off
	s_and_b64 vcc, exec, s[4:5]
	v_mov_b32_e32 v103, 1.0
	v_pk_mul_f32 v[94:95], v[88:89], v[114:115]
	v_pk_mul_f32 v[96:97], v[86:87], v[112:113]
	v_pk_fma_f32 v[94:95], v[92:93], v[110:111], v[94:95] neg_lo:[0,0,1] neg_hi:[0,0,1]
	v_pk_fma_f32 v[96:97], v[90:91], v[108:109], v[96:97] neg_lo:[0,0,1] neg_hi:[0,0,1]
	v_pk_mul_f32 v[92:93], v[92:93], v[114:115]
	v_pk_mul_f32 v[90:91], v[90:91], v[112:113]
	v_pk_fma_f32 v[92:93], v[88:89], v[110:111], v[92:93]
	v_pk_fma_f32 v[88:89], v[86:87], v[108:109], v[90:91]
	v_cvt_pk_bf16_f32 v86, v96, v97
	v_cvt_pk_bf16_f32 v87, v94, v95
	v_mov_b32_e32 v107, 0
	v_cvt_pk_bf16_f32 v88, v88, v89
	v_cvt_pk_bf16_f32 v89, v92, v93
	global_store_dwordx4 v[104:105], v[86:89], off offset:256
	v_mov_b32_e32 v104, 1.0
	v_mov_b32_e32 v105, 1.0
	v_or_b32_e32 v86, 48, v166
	v_mov_b32_e32 v108, 0
	v_mov_b32_e32 v109, 0
	s_cbranch_vccnz .LBB0_425
	s_waitcnt vmcnt(14)
	v_mov_b32_e32 v102, v212
	v_mov_b32_e32 v103, v213
	v_mov_b32_e32 v104, v214
	v_mov_b32_e32 v105, v215
	v_mov_b32_e32 v106, v216
	v_mov_b32_e32 v107, v217
	v_mov_b32_e32 v108, v218
	v_mov_b32_e32 v109, v219
.LBB0_425:
	v_pk_mul_f32 v[88:89], v[80:81], v[108:109]
	v_pk_mul_f32 v[90:91], v[78:79], v[106:107]
	v_pk_fma_f32 v[88:89], v[84:85], v[104:105], v[88:89] neg_lo:[0,0,1] neg_hi:[0,0,1]
	v_pk_fma_f32 v[90:91], v[82:83], v[102:103], v[90:91] neg_lo:[0,0,1] neg_hi:[0,0,1]
	v_pk_mul_f32 v[84:85], v[84:85], v[108:109]
	v_pk_mul_f32 v[82:83], v[82:83], v[106:107]
	v_mad_i64_i32 v[86:87], s[50:51], s19, v86, 0
	v_pk_fma_f32 v[84:85], v[80:81], v[104:105], v[84:85]
	v_pk_fma_f32 v[80:81], v[78:79], v[102:103], v[82:83]
	v_lshl_add_u64 v[86:87], v[86:87], 1, v[162:163]
	v_cvt_pk_bf16_f32 v78, v90, v91
	v_cvt_pk_bf16_f32 v79, v88, v89
	v_cvt_pk_bf16_f32 v80, v80, v81
	v_cvt_pk_bf16_f32 v81, v84, v85
	global_store_dwordx4 v[86:87], v[78:81], off
	s_and_b64 vcc, exec, s[4:5]
	v_mov_b32_e32 v82, 0
	v_pk_mul_f32 v[78:79], v[72:73], v[108:109]
	v_pk_mul_f32 v[80:81], v[70:71], v[106:107]
	v_pk_fma_f32 v[78:79], v[76:77], v[104:105], v[78:79] neg_lo:[0,0,1] neg_hi:[0,0,1]
	v_pk_fma_f32 v[80:81], v[74:75], v[102:103], v[80:81] neg_lo:[0,0,1] neg_hi:[0,0,1]
	v_pk_mul_f32 v[76:77], v[76:77], v[108:109]
	v_pk_mul_f32 v[74:75], v[74:75], v[106:107]
	v_pk_fma_f32 v[76:77], v[72:73], v[104:105], v[76:77]
	v_pk_fma_f32 v[72:73], v[70:71], v[102:103], v[74:75]
	v_cvt_pk_bf16_f32 v70, v80, v81
	v_cvt_pk_bf16_f32 v71, v78, v79
	v_mov_b32_e32 v74, 0
	v_cvt_pk_bf16_f32 v72, v72, v73
	v_cvt_pk_bf16_f32 v73, v76, v77
	global_store_dwordx4 v[86:87], v[70:73], off offset:256
	v_mov_b32_e32 v76, 1.0
	v_mov_b32_e32 v77, 1.0
	v_add_u32_e32 v71, 0x80, v166
	v_mov_b32_e32 v70, 1.0
	v_mov_b32_e32 v78, 1.0
	v_mov_b32_e32 v79, 1.0
	v_mov_b32_e32 v80, 0
	v_mov_b32_e32 v81, 0
	v_mov_b32_e32 v83, 0
	s_cbranch_vccnz .LBB0_427
	s_waitcnt vmcnt(14)
	v_mov_b32_e32 v76, v220
	v_mov_b32_e32 v77, v221
	v_mov_b32_e32 v78, v222
	v_mov_b32_e32 v79, v223
	v_mov_b32_e32 v80, v224
	v_mov_b32_e32 v81, v225
	v_mov_b32_e32 v82, v226
	v_mov_b32_e32 v83, v227
; __device__ __forceinline__ u32x4 pack8(const f32x4 a, const f32x4 b) { u32x4 w; w.x = cvt_pk_bf16(a[0], a[1]); w.y = cvt_pk_bf16(a[2], a[3]); w.z = cvt_pk_bf16(b[0], b[1]); w.w = cvt_pk_bf16(b[2], b[3]); return w; }
;     __device__ __forceinline__ void operator()(const f32x4 (&acc)[2][2][4][2], const Unit& u, int wr, int wc, int fr, int fq) const {
;     ...
;         for (int ai = 0; ai < 2; ++ai)
; #pragma unroll
;             for (int m = 0; m < 4; ++m) { const int row = row0 + ai * HALF + m * 16; bf16_t* rowp = base + (size_t)row * ld + col0;
;                 f32x4 c = (f32x4){1.f, 1.f, 1.f, 1.f}, s = (f32x4){0.f, 0.f, 0.f, 0.f};
;                 if (rope) { const int pos = row & smask; c = *(const f32x4*)(cosT + pos * 32 + dq); s = *(const f32x4*)(sinT + pos * 32 + dq); }
; #pragma unroll
;                 for (int bj = 0; bj < 2; ++bj) { const f32x4 x1 = acc[ai][bj][m][0], x2 = acc[ai][bj][m][1];
;                     const f32x4 o1 = x1 * c - x2 * s, o2 = x2 * c + x1 * s;
;                     *(u32x4*)(rowp + bj * HALF) = pack8(o1, o2); } }
.LBB0_427:
	v_pk_mul_f32 v[84:85], v[64:65], v[82:83]
	v_pk_mul_f32 v[86:87], v[62:63], v[80:81]
	v_pk_fma_f32 v[84:85], v[68:69], v[78:79], v[84:85] neg_lo:[0,0,1] neg_hi:[0,0,1]
	v_pk_fma_f32 v[86:87], v[66:67], v[76:77], v[86:87] neg_lo:[0,0,1] neg_hi:[0,0,1]
	v_pk_mul_f32 v[68:69], v[68:69], v[82:83]
	v_pk_mul_f32 v[66:67], v[66:67], v[80:81]
	v_mad_i64_i32 v[72:73], s[50:51], s19, v71, 0
	v_pk_fma_f32 v[68:69], v[64:65], v[78:79], v[68:69]
	v_pk_fma_f32 v[64:65], v[62:63], v[76:77], v[66:67]
	v_lshl_add_u64 v[72:73], v[72:73], 1, v[162:163]
	v_cvt_pk_bf16_f32 v62, v86, v87
	v_cvt_pk_bf16_f32 v63, v84, v85
	v_cvt_pk_bf16_f32 v64, v64, v65
	v_cvt_pk_bf16_f32 v65, v68, v69
	global_store_dwordx4 v[72:73], v[62:65], off
	s_and_b64 vcc, exec, s[4:5]
	v_mov_b32_e32 v71, 1.0
	v_pk_mul_f32 v[62:63], v[56:57], v[82:83]
	v_pk_mul_f32 v[64:65], v[54:55], v[80:81]
	v_pk_fma_f32 v[62:63], v[60:61], v[78:79], v[62:63] neg_lo:[0,0,1] neg_hi:[0,0,1]
	v_pk_fma_f32 v[64:65], v[58:59], v[76:77], v[64:65] neg_lo:[0,0,1] neg_hi:[0,0,1]
	v_pk_mul_f32 v[60:61], v[60:61], v[82:83]
	v_pk_mul_f32 v[58:59], v[58:59], v[80:81]
	v_pk_fma_f32 v[60:61], v[56:57], v[78:79], v[60:61]
	v_pk_fma_f32 v[56:57], v[54:55], v[76:77], v[58:59]
	v_cvt_pk_bf16_f32 v54, v64, v65
	v_cvt_pk_bf16_f32 v55, v62, v63
	v_mov_b32_e32 v75, 0
	v_cvt_pk_bf16_f32 v56, v56, v57
	v_cvt_pk_bf16_f32 v57, v60, v61
	global_store_dwordx4 v[72:73], v[54:57], off offset:256
	v_mov_b32_e32 v72, 1.0
	v_mov_b32_e32 v73, 1.0
	v_add_u32_e32 v54, 0x90, v166
	v_mov_b32_e32 v76, 0
	v_mov_b32_e32 v77, 0
	s_cbranch_vccnz .LBB0_429
	s_waitcnt vmcnt(14)
	v_mov_b32_e32 v70, v228
	v_mov_b32_e32 v71, v229
	v_mov_b32_e32 v72, v230
	v_mov_b32_e32 v73, v231
	v_mov_b32_e32 v74, v232
	v_mov_b32_e32 v75, v233
	v_mov_b32_e32 v76, v234
	v_mov_b32_e32 v77, v235
.LBB0_429:
	v_pk_mul_f32 v[56:57], v[48:49], v[76:77]
	v_pk_mul_f32 v[58:59], v[46:47], v[74:75]
	v_pk_fma_f32 v[56:57], v[52:53], v[72:73], v[56:57] neg_lo:[0,0,1] neg_hi:[0,0,1]
	v_pk_fma_f32 v[58:59], v[50:51], v[70:71], v[58:59] neg_lo:[0,0,1] neg_hi:[0,0,1]
	v_pk_mul_f32 v[52:53], v[52:53], v[76:77]
	v_pk_mul_f32 v[50:51], v[50:51], v[74:75]
	v_mad_i64_i32 v[54:55], s[50:51], s19, v54, 0
	v_pk_fma_f32 v[52:53], v[48:49], v[72:73], v[52:53]
	v_pk_fma_f32 v[48:49], v[46:47], v[70:71], v[50:51]
	v_lshl_add_u64 v[54:55], v[54:55], 1, v[162:163]
	v_cvt_pk_bf16_f32 v46, v58, v59
	v_cvt_pk_bf16_f32 v47, v56, v57
	v_cvt_pk_bf16_f32 v48, v48, v49
	v_cvt_pk_bf16_f32 v49, v52, v53
	global_store_dwordx4 v[54:55], v[46:49], off
	s_and_b64 vcc, exec, s[4:5]
	v_mov_b32_e32 v50, 0
	v_pk_mul_f32 v[46:47], v[40:41], v[76:77]
	v_pk_mul_f32 v[48:49], v[38:39], v[74:75]
	v_pk_fma_f32 v[46:47], v[44:45], v[72:73], v[46:47] neg_lo:[0,0,1] neg_hi:[0,0,1]
	v_pk_fma_f32 v[48:49], v[42:43], v[70:71], v[48:49] neg_lo:[0,0,1] neg_hi:[0,0,1]
	v_pk_mul_f32 v[44:45], v[44:45], v[76:77]
	v_pk_mul_f32 v[42:43], v[42:43], v[74:75]
	v_pk_fma_f32 v[44:45], v[40:41], v[72:73], v[44:45]
	v_pk_fma_f32 v[40:41], v[38:39], v[70:71], v[42:43]
	v_cvt_pk_bf16_f32 v38, v48, v49
	v_cvt_pk_bf16_f32 v39, v46, v47
	v_mov_b32_e32 v42, 0
	v_cvt_pk_bf16_f32 v40, v40, v41
	v_cvt_pk_bf16_f32 v41, v44, v45
	global_store_dwordx4 v[54:55], v[38:41], off offset:256
	v_mov_b32_e32 v44, 1.0
	v_mov_b32_e32 v45, 1.0
	v_add_u32_e32 v39, 0xa0, v166
	v_mov_b32_e32 v38, 1.0
	v_mov_b32_e32 v46, 1.0
	v_mov_b32_e32 v47, 1.0
	v_mov_b32_e32 v48, 0
	v_mov_b32_e32 v49, 0
	v_mov_b32_e32 v51, 0
	s_cbranch_vccnz .LBB0_431
	s_waitcnt vmcnt(14)
	v_mov_b32_e32 v44, v236
	v_mov_b32_e32 v45, v237
	v_mov_b32_e32 v46, v238
	v_mov_b32_e32 v47, v239
	v_mov_b32_e32 v48, v240
	v_mov_b32_e32 v49, v241
	v_mov_b32_e32 v50, v242
	v_mov_b32_e32 v51, v243
.LBB0_431:
	v_pk_mul_f32 v[52:53], v[32:33], v[50:51]
	v_pk_mul_f32 v[54:55], v[30:31], v[48:49]
	v_pk_fma_f32 v[52:53], v[36:37], v[46:47], v[52:53] neg_lo:[0,0,1] neg_hi:[0,0,1]
	v_pk_fma_f32 v[54:55], v[34:35], v[44:45], v[54:55] neg_lo:[0,0,1] neg_hi:[0,0,1]
	v_pk_mul_f32 v[36:37], v[36:37], v[50:51]
	v_pk_mul_f32 v[34:35], v[34:35], v[48:49]
	v_mad_i64_i32 v[40:41], s[50:51], s19, v39, 0
	v_pk_fma_f32 v[36:37], v[32:33], v[46:47], v[36:37]
	v_pk_fma_f32 v[32:33], v[30:31], v[44:45], v[34:35]
	v_lshl_add_u64 v[40:41], v[40:41], 1, v[162:163]
	v_cvt_pk_bf16_f32 v30, v54, v55
	v_cvt_pk_bf16_f32 v31, v52, v53
	v_cvt_pk_bf16_f32 v32, v32, v33
	v_cvt_pk_bf16_f32 v33, v36, v37
	global_store_dwordx4 v[40:41], v[30:33], off
	s_and_b64 vcc, exec, s[4:5]
	v_mov_b32_e32 v39, 1.0
	v_pk_mul_f32 v[30:31], v[24:25], v[50:51]
	v_pk_mul_f32 v[32:33], v[22:23], v[48:49]
	v_pk_fma_f32 v[30:31], v[28:29], v[46:47], v[30:31] neg_lo:[0,0,1] neg_hi:[0,0,1]
	v_pk_fma_f32 v[32:33], v[26:27], v[44:45], v[32:33] neg_lo:[0,0,1] neg_hi:[0,0,1]
	v_pk_mul_f32 v[28:29], v[28:29], v[50:51]
	v_pk_mul_f32 v[26:27], v[26:27], v[48:49]
	v_pk_fma_f32 v[28:29], v[24:25], v[46:47], v[28:29]
	v_pk_fma_f32 v[24:25], v[22:23], v[44:45], v[26:27]
	v_cvt_pk_bf16_f32 v22, v32, v33
	v_cvt_pk_bf16_f32 v23, v30, v31
	v_mov_b32_e32 v43, 0
	v_cvt_pk_bf16_f32 v24, v24, v25
	v_cvt_pk_bf16_f32 v25, v28, v29
	global_store_dwordx4 v[40:41], v[22:25], off offset:256
	v_mov_b32_e32 v40, 1.0
	v_mov_b32_e32 v41, 1.0
	v_add_u32_e32 v22, 0xb0, v166
	v_mov_b32_e32 v44, 0
	v_mov_b32_e32 v45, 0
	s_cbranch_vccnz .LBB0_433
	s_waitcnt vmcnt(12)
	v_mov_b32_e32 v38, v188
	v_mov_b32_e32 v39, v189
	v_mov_b32_e32 v40, v190
	v_mov_b32_e32 v41, v191
	v_mov_b32_e32 v42, v192
	v_mov_b32_e32 v43, v193
	v_mov_b32_e32 v44, v194
	v_mov_b32_e32 v45, v195
.LBB0_433:
	v_pk_mul_f32 v[24:25], v[12:13], v[44:45]
	v_pk_mul_f32 v[26:27], v[10:11], v[42:43]
	v_pk_fma_f32 v[24:25], v[20:21], v[40:41], v[24:25] neg_lo:[0,0,1] neg_hi:[0,0,1]
	v_pk_fma_f32 v[26:27], v[18:19], v[38:39], v[26:27] neg_lo:[0,0,1] neg_hi:[0,0,1]
	v_pk_mul_f32 v[20:21], v[20:21], v[44:45]
	v_pk_mul_f32 v[18:19], v[18:19], v[42:43]
	v_mad_i64_i32 v[22:23], s[4:5], s19, v22, 0
	v_pk_fma_f32 v[20:21], v[12:13], v[40:41], v[20:21]
	v_pk_fma_f32 v[12:13], v[10:11], v[38:39], v[18:19]
	v_lshl_add_u64 v[22:23], v[22:23], 1, v[162:163]
	v_cvt_pk_bf16_f32 v10, v26, v27
	v_cvt_pk_bf16_f32 v11, v24, v25
	v_cvt_pk_bf16_f32 v12, v12, v13
	v_cvt_pk_bf16_f32 v13, v20, v21
	global_store_dwordx4 v[22:23], v[10:13], off
	s_andn2_b64 vcc, exec, s[0:1]
	s_mov_b64 s[0:1], -1
	v_pk_mul_f32 v[10:11], v[4:5], v[44:45]
	v_pk_mul_f32 v[12:13], v[2:3], v[42:43]
	v_pk_fma_f32 v[10:11], v[8:9], v[40:41], v[10:11] neg_lo:[0,0,1] neg_hi:[0,0,1]
	v_pk_fma_f32 v[12:13], v[6:7], v[38:39], v[12:13] neg_lo:[0,0,1] neg_hi:[0,0,1]
	v_pk_mul_f32 v[8:9], v[8:9], v[44:45]
	v_pk_mul_f32 v[6:7], v[6:7], v[42:43]
	v_pk_fma_f32 v[8:9], v[4:5], v[40:41], v[8:9]
	v_pk_fma_f32 v[4:5], v[2:3], v[38:39], v[6:7]
	v_cvt_pk_bf16_f32 v2, v12, v13
	v_cvt_pk_bf16_f32 v3, v10, v11
	s_nop 0
	v_cvt_pk_bf16_f32 v4, v4, v5
	v_cvt_pk_bf16_f32 v5, v8, v9
	global_store_dwordx4 v[22:23], v[2:5], off offset:256
	s_cbranch_vccnz .LBB0_403
	s_andn2_b64 vcc, exec, s[2:3]
	s_cbranch_vccnz .LBB0_402
	s_barrier
	s_branch .LBB0_402
